# attention softmax: dropped the redundant canonicalising max on the running maximum and merged the first two row-sum adds (2 VALU ops fewer per query group per key tile)
# speedup vs baseline: 1.0032x; 1.0032x over previous
; #define MFMA32(a, b, c) __builtin_amdgcn_mfma_f32_32x32x16_bf16((a), (b), (c), 0, 0, 0)
;     ...
;   for (int kt = 0; kt < nkt; ++kt) {
;     __syncthreads();
; #pragma unroll
;     for (int i = 0; i < 3; ++i) {
;       int c = tid + 256 * i, key = c / 12, part = c % 12;
;       *(u32x4*)(Ks + key * 104 + part * 8) = rk[i];
;     }
; #pragma unroll
;     for (int i = 0; i < 2; ++i) {
;       int c = tid + 256 * i, dv = c >> 3, part = c & 7;
;       *(u32x2*)(Vs + dv * 68 + part * 8) = mk2(rv[i].x, rv[i].y);
;       *(u32x2*)(Vs + dv * 68 + part * 8 + 4) = mk2(rv[i].z, rv[i].w);
;     }
;     __syncthreads();
;     if (kt + 1 < nkt) loadt(kt + 1);
;     f32x16 S[2][2];
; #pragma unroll
;     for (int g = 0; g < 2; ++g) { zero_acc(S[g][0]); zero_acc(S[g][1]); }
; #pragma unroll
;     for (int mt = 0; mt < 2; ++mt)
; #pragma unroll
;       for (int s = 0; s < 6; ++s) {
;         const bf16x8 a = *(const bf16x8*)(Ks + (mt * 32 + l31) * 104 + s * 16 + hh * 8);
;         S[0][mt] = MFMA32(a, qf[0][s], S[0][mt]);
;         S[1][mt] = MFMA32(a, qf[1][s], S[1][mt]);
;       }
;     asm volatile("s_nop 15\n\ts_nop 15" ::: "memory");
; #pragma unroll
;     for (int g = 0; g < 2; ++g) {
;       float mx = -1e30f;
; #pragma unroll
;       for (int mt = 0; mt < 2; ++mt)
; #pragma unroll
;         for (int r = 0; r < 16; ++r) mx = fmaxf(mx, S[g][mt][r]);
;       mx = fmaxf(mx, __shfl_xor(mx, 32)) * scl;
;       const float mnew = fmaxf(mrun[g], mx);
;       const float alpha = __builtin_amdgcn_exp2f(mrun[g] - mnew);
;       mrun[g] = mnew;
;       float ps = 0.f;
; #pragma unroll
;       for (int mt = 0; mt < 2; ++mt)
; #pragma unroll
;         for (int r = 0; r < 16; ++r) { float e = __builtin_amdgcn_exp2f(fmaf(S[g][mt][r], scl, -mnew)); S[g][mt][r] = e; ps += e; }
;       lsum[g] = lsum[g] * alpha + ps;
;       if (__builtin_amdgcn_ballot_w64(alpha != 1.f) != 0ull) {
; #pragma unroll
;         for (int d = 0; d < 2; ++d)
; #pragma unroll
;           for (int r = 0; r < 16; ++r) O[g][d][r] *= alpha;
;       }
;     }
.Latt_kt:
	v_lshl_add_u64 v[220:221], s[8:9], 0, v[212:213]
	s_barrier
	s_waitcnt vmcnt(4)
	ds_write_b128 v239, v[178:181]
	s_waitcnt vmcnt(3)
	ds_write_b128 v240, v[182:185]
	s_waitcnt vmcnt(2)
	ds_write_b128 v241, v[186:189]
	s_waitcnt vmcnt(1)
	ds_write2_b64 v242, v[190:191], v[192:193] offset1:1
	s_waitcnt vmcnt(0)
	ds_write2_b64 v243, v[194:195], v[196:197] offset1:1
	s_waitcnt lgkmcnt(0)
	s_barrier
	global_load_dwordx4 v[178:181], v[220:221], off
	v_lshl_add_u64 v[220:221], s[8:9], 0, v[210:211]
	global_load_dwordx4 v[182:185], v[220:221], off
	v_lshl_add_u64 v[220:221], s[8:9], 0, v[208:209]
	global_load_dwordx4 v[186:189], v[220:221], off
	v_lshl_add_u64 v[220:221], s[8:9], 0, v[206:207]
	global_load_dwordx4 v[190:193], v[220:221], off
	v_lshl_add_u64 v[220:221], s[8:9], 0, v[204:205]
	global_load_dwordx4 v[194:197], v[220:221], off
	ds_read_b128 v[220:223], v238
	ds_read_b128 v[224:227], v238 offset:6656
	ds_read_b128 v[230:233], v238 offset:32
	s_waitcnt lgkmcnt(2)
	v_mfma_f32_32x32x16_bf16 v[66:81], v[220:223], v[170:173], 0
	ds_read_b128 v[220:223], v238 offset:6688
	s_waitcnt lgkmcnt(2)
	v_mfma_f32_32x32x16_bf16 v[82:97], v[224:227], v[170:173], 0
	ds_read_b128 v[224:227], v238 offset:64
	s_waitcnt lgkmcnt(2)
	v_mfma_f32_32x32x16_bf16 v[66:81], v[230:233], v[158:161], v[66:81]
	ds_read_b128 v[230:233], v238 offset:6720
	s_waitcnt lgkmcnt(2)
	v_mfma_f32_32x32x16_bf16 v[82:97], v[220:223], v[158:161], v[82:97]
	ds_read_b128 v[220:223], v238 offset:96
	s_waitcnt lgkmcnt(2)
	v_mfma_f32_32x32x16_bf16 v[66:81], v[224:227], v[154:157], v[66:81]
	ds_read_b128 v[224:227], v238 offset:6752
	s_waitcnt lgkmcnt(2)
	v_mfma_f32_32x32x16_bf16 v[82:97], v[230:233], v[154:157], v[82:97]
	ds_read_b128 v[230:233], v238 offset:128
	s_waitcnt lgkmcnt(2)
	v_mfma_f32_32x32x16_bf16 v[66:81], v[220:223], v[142:145], v[66:81]
	ds_read_b128 v[220:223], v238 offset:6784
	s_waitcnt lgkmcnt(2)
	v_mfma_f32_32x32x16_bf16 v[82:97], v[224:227], v[142:145], v[82:97]
	ds_read_b128 v[224:227], v238 offset:160
	s_waitcnt lgkmcnt(2)
	v_mfma_f32_32x32x16_bf16 v[66:81], v[230:233], v[138:141], v[66:81]
	ds_read_b128 v[230:233], v238 offset:6816
	s_waitcnt lgkmcnt(2)
	v_mfma_f32_32x32x16_bf16 v[82:97], v[220:223], v[138:141], v[82:97]
	s_waitcnt lgkmcnt(1)
	v_mfma_f32_32x32x16_bf16 v[66:81], v[224:227], v[130:133], v[66:81]
	s_waitcnt lgkmcnt(0)
	v_mfma_f32_32x32x16_bf16 v[82:97], v[230:233], v[130:133], v[82:97]
	ds_read_b128 v[220:223], v238
	ds_read_b128 v[224:227], v238 offset:6656
	ds_read_b128 v[230:233], v238 offset:32
	s_waitcnt lgkmcnt(2)
	v_mfma_f32_32x32x16_bf16 v[98:113], v[220:223], v[174:177], 0
	ds_read_b128 v[220:223], v238 offset:6688
	s_waitcnt lgkmcnt(2)
	v_mfma_f32_32x32x16_bf16 v[114:129], v[224:227], v[174:177], 0
	s_nop 7
	v_max3_f32 v251, v66, s63, v67
	v_max3_f32 v254, v68, s63, v69
	v_max3_f32 v251, v251, v70, v71
	v_max3_f32 v254, v254, v72, v73
	v_max3_f32 v251, v251, v74, v75
	v_max3_f32 v254, v254, v76, v77
	v_max3_f32 v251, v251, v78, v79
	v_max3_f32 v254, v254, v80, v81
	v_max3_f32 v251, v251, v82, v83
	v_max3_f32 v254, v254, v84, v85
	v_max3_f32 v251, v251, v86, v87
	v_max3_f32 v254, v254, v88, v89
	v_max3_f32 v251, v251, v90, v91
	ds_read_b128 v[224:227], v238 offset:64
	s_waitcnt lgkmcnt(2)
	v_mfma_f32_32x32x16_bf16 v[98:113], v[230:233], v[166:169], v[98:113]
	v_max3_f32 v254, v254, v92, v93
	v_max3_f32 v251, v251, v94, v95
	v_max3_f32 v254, v254, v96, v97
	v_max_f32_e32 v251, v251, v254
	v_mov_b32_e32 v254, v251
	s_nop 1
	v_permlane32_swap_b32_e32 v254, v251
	v_max_f32_e32 v251, v251, v254
	v_mul_f32_e32 v251, 0x3e16c740, v251
	v_max_f32_e32 v251, v246, v251
	v_sub_f32_e32 v236, v246, v251
	v_exp_f32_e32 v236, v236
	v_mov_b32_e32 v246, v251
	v_cmp_neq_f32_e32 vcc, 1.0, v236
	s_cbranch_vccz .Latt_noscale0
	v_pk_mul_f32 v[50:51], v[50:51], v[236:237] op_sel_hi:[1,0]
	v_pk_mul_f32 v[52:53], v[52:53], v[236:237] op_sel_hi:[1,0]
	v_pk_mul_f32 v[54:55], v[54:55], v[236:237] op_sel_hi:[1,0]
	v_pk_mul_f32 v[56:57], v[56:57], v[236:237] op_sel_hi:[1,0]
	v_pk_mul_f32 v[58:59], v[58:59], v[236:237] op_sel_hi:[1,0]
	v_pk_mul_f32 v[60:61], v[60:61], v[236:237] op_sel_hi:[1,0]
	v_pk_mul_f32 v[62:63], v[62:63], v[236:237] op_sel_hi:[1,0]
	v_pk_mul_f32 v[64:65], v[64:65], v[236:237] op_sel_hi:[1,0]
	v_pk_mul_f32 v[34:35], v[34:35], v[236:237] op_sel_hi:[1,0]
	v_pk_mul_f32 v[36:37], v[36:37], v[236:237] op_sel_hi:[1,0]
	v_pk_mul_f32 v[38:39], v[38:39], v[236:237] op_sel_hi:[1,0]
	v_pk_mul_f32 v[40:41], v[40:41], v[236:237] op_sel_hi:[1,0]
	v_pk_mul_f32 v[42:43], v[42:43], v[236:237] op_sel_hi:[1,0]
	v_pk_mul_f32 v[44:45], v[44:45], v[236:237] op_sel_hi:[1,0]
	v_pk_mul_f32 v[46:47], v[46:47], v[236:237] op_sel_hi:[1,0]
	v_pk_mul_f32 v[48:49], v[48:49], v[236:237] op_sel_hi:[1,0]
; #define MFMA32(a, b, c) __builtin_amdgcn_mfma_f32_32x32x16_bf16((a), (b), (c), 0, 0, 0)
; DI unsigned pack2(float lo, float hi) { f32x2 v; v.x = lo; v.y = hi; return __builtin_bit_cast(unsigned, __builtin_convertvector(v, hwbf2)); }
;     ...
;       const float mnew = fmaxf(mrun[g], mx);
;       const float alpha = __builtin_amdgcn_exp2f(mrun[g] - mnew);
;       mrun[g] = mnew;
;       float ps = 0.f;
; #pragma unroll
;       for (int mt = 0; mt < 2; ++mt)
; #pragma unroll
;         for (int r = 0; r < 16; ++r) { float e = __builtin_amdgcn_exp2f(fmaf(S[g][mt][r], scl, -mnew)); S[g][mt][r] = e; ps += e; }
;       lsum[g] = lsum[g] * alpha + ps;
;       if (__builtin_amdgcn_ballot_w64(alpha != 1.f) != 0ull) {
; #pragma unroll
;         for (int d = 0; d < 2; ++d)
; #pragma unroll
;           for (int r = 0; r < 16; ++r) O[g][d][r] *= alpha;
;       }
;     }
; #pragma unroll
;     for (int mt = 0; mt < 2; ++mt)
; #pragma unroll
;       for (int s2 = 0; s2 < 2; ++s2) {
;         bf16x8 pf[2];
; #pragma unroll
;         for (int g = 0; g < 2; ++g) {
;           unsigned pk[4];
; #pragma unroll
;           for (int q = 0; q < 4; ++q) pk[q] = pack2(S[g][mt][8 * s2 + 2 * q], S[g][mt][8 * s2 + 2 * q + 1]);
;           pf[g] = __builtin_bit_cast(bf16x8, (u32x4{pk[0], pk[1], pk[2], pk[3]}));
;         }
; #pragma unroll
;         for (int d = 0; d < 2; ++d) {
;           const u16* vp = Vs + (d * 32 + l31) * 68 + mt * 32 + s2 * 16 + 4 * hh;
;           u32x2 lo = *(const u32x2*)vp, hi = *(const u32x2*)(vp + 8);
;           const bf16x8 va = __builtin_bit_cast(bf16x8, (u32x4{lo.x, lo.y, hi.x, hi.y}));
;           O[0][d] = MFMA32(va, pf[0], O[0][d]);
;           O[1][d] = MFMA32(va, pf[1], O[1][d]);
;         }
.Latt_noscale0:
	v_fma_f32 v66, v66, s56, -v251
	v_fma_f32 v67, v67, s56, -v251
	v_exp_f32_e32 v66, v66
	ds_read_b128 v[230:233], v238 offset:6720
	s_waitcnt lgkmcnt(2)
	v_mfma_f32_32x32x16_bf16 v[114:129], v[220:223], v[166:169], v[114:129]
	v_exp_f32_e32 v67, v67
	v_fma_f32 v68, v68, s56, -v251
	v_fma_f32 v69, v69, s56, -v251
	v_add_f32_e32 v254, v66, v67
	v_exp_f32_e32 v68, v68
	v_exp_f32_e32 v69, v69
	v_fma_f32 v70, v70, s56, -v251
	v_add_f32_e32 v254, v68, v254
	v_fma_f32 v71, v71, s56, -v251
	v_add_f32_e32 v254, v69, v254
	v_exp_f32_e32 v70, v70
	v_exp_f32_e32 v71, v71
	v_fma_f32 v72, v72, s56, -v251
	ds_read_b128 v[220:223], v238 offset:96
	s_waitcnt lgkmcnt(2)
	v_mfma_f32_32x32x16_bf16 v[98:113], v[224:227], v[162:165], v[98:113]
	v_add_f32_e32 v254, v70, v254
	v_fma_f32 v73, v73, s56, -v251
	v_add_f32_e32 v254, v71, v254
	v_exp_f32_e32 v72, v72
	v_exp_f32_e32 v73, v73
	v_fma_f32 v74, v74, s56, -v251
	v_add_f32_e32 v254, v72, v254
	v_fma_f32 v75, v75, s56, -v251
	v_add_f32_e32 v254, v73, v254
	v_exp_f32_e32 v74, v74
	v_exp_f32_e32 v75, v75
	v_fma_f32 v76, v76, s56, -v251
	v_add_f32_e32 v254, v74, v254
	v_fma_f32 v77, v77, s56, -v251
	ds_read_b128 v[224:227], v238 offset:6752
	s_waitcnt lgkmcnt(2)
	v_mfma_f32_32x32x16_bf16 v[114:129], v[230:233], v[162:165], v[114:129]
	v_add_f32_e32 v254, v75, v254
	v_exp_f32_e32 v76, v76
	v_exp_f32_e32 v77, v77
	v_fma_f32 v78, v78, s56, -v251
	v_add_f32_e32 v254, v76, v254
	v_fma_f32 v79, v79, s56, -v251
	v_add_f32_e32 v254, v77, v254
	v_exp_f32_e32 v78, v78
	v_exp_f32_e32 v79, v79
	v_fma_f32 v80, v80, s56, -v251
	v_add_f32_e32 v254, v78, v254
	v_fma_f32 v81, v81, s56, -v251
	v_add_f32_e32 v254, v79, v254
	v_exp_f32_e32 v80, v80
	ds_read_b128 v[230:233], v238 offset:128
	s_waitcnt lgkmcnt(2)
	v_mfma_f32_32x32x16_bf16 v[98:113], v[220:223], v[150:153], v[98:113]
	v_exp_f32_e32 v81, v81
	v_fma_f32 v82, v82, s56, -v251
	v_add_f32_e32 v254, v80, v254
	v_fma_f32 v83, v83, s56, -v251
	v_add_f32_e32 v254, v81, v254
	v_exp_f32_e32 v82, v82
	v_exp_f32_e32 v83, v83
	v_fma_f32 v84, v84, s56, -v251
	v_add_f32_e32 v254, v82, v254
	v_fma_f32 v85, v85, s56, -v251
	v_add_f32_e32 v254, v83, v254
	v_exp_f32_e32 v84, v84
	v_exp_f32_e32 v85, v85
	ds_read_b128 v[220:223], v238 offset:6784
	s_waitcnt lgkmcnt(2)
	v_mfma_f32_32x32x16_bf16 v[114:129], v[224:227], v[150:153], v[114:129]
	v_fma_f32 v86, v86, s56, -v251
	v_add_f32_e32 v254, v84, v254
	v_fma_f32 v87, v87, s56, -v251
	v_add_f32_e32 v254, v85, v254
	v_exp_f32_e32 v86, v86
	v_exp_f32_e32 v87, v87
	v_fma_f32 v88, v88, s56, -v251
	v_add_f32_e32 v254, v86, v254
	v_fma_f32 v89, v89, s56, -v251
	v_add_f32_e32 v254, v87, v254
	v_exp_f32_e32 v88, v88
	v_exp_f32_e32 v89, v89
	v_fma_f32 v90, v90, s56, -v251
	v_add_f32_e32 v254, v88, v254
	ds_read_b128 v[224:227], v238 offset:160
	s_waitcnt lgkmcnt(2)
	v_mfma_f32_32x32x16_bf16 v[98:113], v[230:233], v[146:149], v[98:113]
	v_fma_f32 v91, v91, s56, -v251
	v_add_f32_e32 v254, v89, v254
	v_exp_f32_e32 v90, v90
	v_exp_f32_e32 v91, v91
	v_fma_f32 v92, v92, s56, -v251
	v_add_f32_e32 v254, v90, v254
	v_fma_f32 v93, v93, s56, -v251
	v_add_f32_e32 v254, v91, v254
	v_exp_f32_e32 v92, v92
	v_exp_f32_e32 v93, v93
	v_fma_f32 v94, v94, s56, -v251
	v_add_f32_e32 v254, v92, v254
	v_fma_f32 v95, v95, s56, -v251
	v_add_f32_e32 v254, v93, v254
	ds_read_b128 v[230:233], v238 offset:6816
	s_waitcnt lgkmcnt(2)
	v_mfma_f32_32x32x16_bf16 v[114:129], v[220:223], v[146:149], v[114:129]
	v_exp_f32_e32 v94, v94
	v_exp_f32_e32 v95, v95
	v_fma_f32 v96, v96, s56, -v251
	v_add_f32_e32 v254, v94, v254
	v_fma_f32 v97, v97, s56, -v251
	v_add_f32_e32 v254, v95, v254
	v_exp_f32_e32 v96, v96
	v_exp_f32_e32 v97, v97
	v_add_f32_e32 v254, v96, v254
	v_add_f32_e32 v254, v97, v254
	v_fmac_f32_e32 v254, v247, v236
	v_mov_b32_e32 v247, v254
	v_cvt_pk_bf16_f32 v66, v66, v67
	v_cvt_pk_bf16_f32 v67, v68, v69
	s_waitcnt lgkmcnt(1)
	v_mfma_f32_32x32x16_bf16 v[98:113], v[224:227], v[134:137], v[98:113]
	v_cvt_pk_bf16_f32 v68, v70, v71
	v_cvt_pk_bf16_f32 v69, v72, v73
	v_cvt_pk_bf16_f32 v70, v74, v75
	v_cvt_pk_bf16_f32 v71, v76, v77
	v_cvt_pk_bf16_f32 v72, v78, v79
	v_cvt_pk_bf16_f32 v73, v80, v81
	v_cvt_pk_bf16_f32 v74, v82, v83
	v_cvt_pk_bf16_f32 v75, v84, v85
	v_cvt_pk_bf16_f32 v76, v86, v87
	v_cvt_pk_bf16_f32 v77, v88, v89
	v_cvt_pk_bf16_f32 v78, v90, v91
	v_cvt_pk_bf16_f32 v79, v92, v93
	v_cvt_pk_bf16_f32 v80, v94, v95
	v_cvt_pk_bf16_f32 v81, v96, v97
	s_waitcnt lgkmcnt(0)
	v_mfma_f32_32x32x16_bf16 v[114:129], v[230:233], v[134:137], v[114:129]
	ds_read2_b64 v[220:223], v214 offset0:128 offset1:130
	ds_read2_b64 v[224:227], v216 offset0:128 offset1:130
	ds_read2_b64 v[230:233], v214 offset0:132 offset1:134
	s_waitcnt lgkmcnt(2)
	v_mfma_f32_32x32x16_bf16 v[50:65], v[220:223], v[66:69], v[50:65]
	s_nop 9
	v_max3_f32 v251, v98, s63, v99
	v_max3_f32 v254, v100, s63, v101
	v_max3_f32 v251, v251, v102, v103
	v_max3_f32 v254, v254, v104, v105
	v_max3_f32 v251, v251, v106, v107
	v_max3_f32 v254, v254, v108, v109
	v_max3_f32 v251, v251, v110, v111
	v_max3_f32 v254, v254, v112, v113
	v_max3_f32 v251, v251, v114, v115
	v_max3_f32 v254, v254, v116, v117
	v_max3_f32 v251, v251, v118, v119
	v_max3_f32 v254, v254, v120, v121
	v_max3_f32 v251, v251, v122, v123
	v_max3_f32 v254, v254, v124, v125
	v_max3_f32 v251, v251, v126, v127
	v_max3_f32 v254, v254, v128, v129
	v_max_f32_e32 v251, v251, v254
	v_mov_b32_e32 v254, v251
	s_nop 1
	v_permlane32_swap_b32_e32 v254, v251
	v_max_f32_e32 v251, v251, v254
	v_mul_f32_e32 v251, 0x3e16c740, v251
	v_max_f32_e32 v251, v249, v251
	ds_read2_b64 v[220:223], v216 offset0:132 offset1:134
	s_waitcnt lgkmcnt(2)
	v_mfma_f32_32x32x16_bf16 v[34:49], v[224:227], v[66:69], v[34:49]
	v_sub_f32_e32 v250, v249, v251
	v_exp_f32_e32 v250, v250
	v_mov_b32_e32 v249, v251
	v_cmp_neq_f32_e32 vcc, 1.0, v250
	s_cbranch_vccz .Latt_noscale1
	v_pk_mul_f32 v[18:19], v[18:19], v[250:251] op_sel_hi:[1,0]
	v_pk_mul_f32 v[20:21], v[20:21], v[250:251] op_sel_hi:[1,0]
	v_pk_mul_f32 v[22:23], v[22:23], v[250:251] op_sel_hi:[1,0]
	v_pk_mul_f32 v[24:25], v[24:25], v[250:251] op_sel_hi:[1,0]
	v_pk_mul_f32 v[26:27], v[26:27], v[250:251] op_sel_hi:[1,0]
	v_pk_mul_f32 v[28:29], v[28:29], v[250:251] op_sel_hi:[1,0]
	v_pk_mul_f32 v[30:31], v[30:31], v[250:251] op_sel_hi:[1,0]
	v_pk_mul_f32 v[32:33], v[32:33], v[250:251] op_sel_hi:[1,0]
	v_pk_mul_f32 v[2:3], v[2:3], v[250:251] op_sel_hi:[1,0]
	v_pk_mul_f32 v[4:5], v[4:5], v[250:251] op_sel_hi:[1,0]
	v_pk_mul_f32 v[6:7], v[6:7], v[250:251] op_sel_hi:[1,0]
	v_pk_mul_f32 v[8:9], v[8:9], v[250:251] op_sel_hi:[1,0]
	v_pk_mul_f32 v[10:11], v[10:11], v[250:251] op_sel_hi:[1,0]
	v_pk_mul_f32 v[12:13], v[12:13], v[250:251] op_sel_hi:[1,0]
	v_pk_mul_f32 v[14:15], v[14:15], v[250:251] op_sel_hi:[1,0]
	v_pk_mul_f32 v[16:17], v[16:17], v[250:251] op_sel_hi:[1,0]
; #define MFMA32(a, b, c) __builtin_amdgcn_mfma_f32_32x32x16_bf16((a), (b), (c), 0, 0, 0)
; DI unsigned pack2(float lo, float hi) { f32x2 v; v.x = lo; v.y = hi; return __builtin_bit_cast(unsigned, __builtin_convertvector(v, hwbf2)); }
;     ...
;       float ps = 0.f;
; #pragma unroll
;       for (int mt = 0; mt < 2; ++mt)
; #pragma unroll
;         for (int r = 0; r < 16; ++r) { float e = __builtin_amdgcn_exp2f(fmaf(S[g][mt][r], scl, -mnew)); S[g][mt][r] = e; ps += e; }
;       lsum[g] = lsum[g] * alpha + ps;
;       if (__builtin_amdgcn_ballot_w64(alpha != 1.f) != 0ull) {
; #pragma unroll
;         for (int d = 0; d < 2; ++d)
; #pragma unroll
;           for (int r = 0; r < 16; ++r) O[g][d][r] *= alpha;
;       }
;     }
; #pragma unroll
;     for (int mt = 0; mt < 2; ++mt)
; #pragma unroll
;       for (int s2 = 0; s2 < 2; ++s2) {
;         bf16x8 pf[2];
; #pragma unroll
;         for (int g = 0; g < 2; ++g) {
;           unsigned pk[4];
; #pragma unroll
;           for (int q = 0; q < 4; ++q) pk[q] = pack2(S[g][mt][8 * s2 + 2 * q], S[g][mt][8 * s2 + 2 * q + 1]);
;           pf[g] = __builtin_bit_cast(bf16x8, (u32x4{pk[0], pk[1], pk[2], pk[3]}));
;         }
; #pragma unroll
;         for (int d = 0; d < 2; ++d) {
;           const u16* vp = Vs + (d * 32 + l31) * 68 + mt * 32 + s2 * 16 + 4 * hh;
;           u32x2 lo = *(const u32x2*)vp, hi = *(const u32x2*)(vp + 8);
;           const bf16x8 va = __builtin_bit_cast(bf16x8, (u32x4{lo.x, lo.y, hi.x, hi.y}));
;           O[0][d] = MFMA32(va, pf[0], O[0][d]);
;           O[1][d] = MFMA32(va, pf[1], O[1][d]);
;         }
;       }
;     asm volatile("s_nop 15\n\ts_nop 15" ::: "memory");
.Latt_noscale1:
	v_fma_f32 v98, v98, s56, -v251
	v_fma_f32 v99, v99, s56, -v251
	v_exp_f32_e32 v98, v98
	v_exp_f32_e32 v99, v99
	v_fma_f32 v100, v100, s56, -v251
	v_fma_f32 v101, v101, s56, -v251
	v_add_f32_e32 v254, v98, v99
	v_exp_f32_e32 v100, v100
	v_exp_f32_e32 v101, v101
	v_fma_f32 v102, v102, s56, -v251
	v_add_f32_e32 v254, v100, v254
	v_fma_f32 v103, v103, s56, -v251
	v_add_f32_e32 v254, v101, v254
	v_exp_f32_e32 v102, v102
	v_exp_f32_e32 v103, v103
	ds_read2_b64 v[224:227], v214 offset0:136 offset1:138
	s_waitcnt lgkmcnt(2)
	v_mfma_f32_32x32x16_bf16 v[50:65], v[230:233], v[70:73], v[50:65]
	v_fma_f32 v104, v104, s56, -v251
	v_add_f32_e32 v254, v102, v254
	v_fma_f32 v105, v105, s56, -v251
	v_add_f32_e32 v254, v103, v254
	v_exp_f32_e32 v104, v104
	v_exp_f32_e32 v105, v105
	v_fma_f32 v106, v106, s56, -v251
	v_add_f32_e32 v254, v104, v254
	v_fma_f32 v107, v107, s56, -v251
	v_add_f32_e32 v254, v105, v254
	v_exp_f32_e32 v106, v106
	v_exp_f32_e32 v107, v107
	v_fma_f32 v108, v108, s56, -v251
	v_add_f32_e32 v254, v106, v254
	v_fma_f32 v109, v109, s56, -v251
	v_add_f32_e32 v254, v107, v254
	v_exp_f32_e32 v108, v108
	v_exp_f32_e32 v109, v109
	v_fma_f32 v110, v110, s56, -v251
	v_add_f32_e32 v254, v108, v254
	v_fma_f32 v111, v111, s56, -v251
	ds_read2_b64 v[230:233], v216 offset0:136 offset1:138
	s_waitcnt lgkmcnt(2)
	v_mfma_f32_32x32x16_bf16 v[34:49], v[220:223], v[70:73], v[34:49]
	v_add_f32_e32 v254, v109, v254
	v_exp_f32_e32 v110, v110
	v_exp_f32_e32 v111, v111
	v_fma_f32 v112, v112, s56, -v251
	v_add_f32_e32 v254, v110, v254
	v_fma_f32 v113, v113, s56, -v251
	v_add_f32_e32 v254, v111, v254
	v_exp_f32_e32 v112, v112
	v_exp_f32_e32 v113, v113
	v_fma_f32 v114, v114, s56, -v251
	v_add_f32_e32 v254, v112, v254
	v_fma_f32 v115, v115, s56, -v251
	v_add_f32_e32 v254, v113, v254
	v_exp_f32_e32 v114, v114
	v_exp_f32_e32 v115, v115
	v_fma_f32 v116, v116, s56, -v251
	v_add_f32_e32 v254, v114, v254
	v_fma_f32 v117, v117, s56, -v251
	v_add_f32_e32 v254, v115, v254
	v_exp_f32_e32 v116, v116
	ds_read2_b64 v[220:223], v214 offset0:140 offset1:142
	s_waitcnt lgkmcnt(2)
	v_mfma_f32_32x32x16_bf16 v[50:65], v[224:227], v[74:77], v[50:65]
	v_exp_f32_e32 v117, v117
	v_fma_f32 v118, v118, s56, -v251
	v_add_f32_e32 v254, v116, v254
	v_fma_f32 v119, v119, s56, -v251
	v_add_f32_e32 v254, v117, v254
	v_exp_f32_e32 v118, v118
	v_exp_f32_e32 v119, v119
	v_fma_f32 v120, v120, s56, -v251
	v_add_f32_e32 v254, v118, v254
	v_fma_f32 v121, v121, s56, -v251
	v_add_f32_e32 v254, v119, v254
	v_exp_f32_e32 v120, v120
	v_exp_f32_e32 v121, v121
	v_fma_f32 v122, v122, s56, -v251
	v_add_f32_e32 v254, v120, v254
	v_fma_f32 v123, v123, s56, -v251
	v_add_f32_e32 v254, v121, v254
	v_exp_f32_e32 v122, v122
	v_exp_f32_e32 v123, v123
	v_fma_f32 v124, v124, s56, -v251
	v_add_f32_e32 v254, v122, v254
	ds_read2_b64 v[224:227], v216 offset0:140 offset1:142
	s_waitcnt lgkmcnt(2)
	v_mfma_f32_32x32x16_bf16 v[34:49], v[230:233], v[74:77], v[34:49]
	v_fma_f32 v125, v125, s56, -v251
	v_add_f32_e32 v254, v123, v254
	v_exp_f32_e32 v124, v124
	v_exp_f32_e32 v125, v125
	v_fma_f32 v126, v126, s56, -v251
	v_add_f32_e32 v254, v124, v254
	v_fma_f32 v127, v127, s56, -v251
	v_add_f32_e32 v254, v125, v254
	v_exp_f32_e32 v126, v126
	v_exp_f32_e32 v127, v127
	v_fma_f32 v128, v128, s56, -v251
	v_add_f32_e32 v254, v126, v254
	v_fma_f32 v129, v129, s56, -v251
	v_add_f32_e32 v254, v127, v254
	v_exp_f32_e32 v128, v128
	v_exp_f32_e32 v129, v129
	v_add_f32_e32 v254, v128, v254
	v_add_f32_e32 v254, v129, v254
	v_fmac_f32_e32 v254, v248, v250
	v_mov_b32_e32 v248, v254
	s_waitcnt lgkmcnt(1)
	v_mfma_f32_32x32x16_bf16 v[50:65], v[220:223], v[78:81], v[50:65]
	v_cvt_pk_bf16_f32 v98, v98, v99
	v_cvt_pk_bf16_f32 v99, v100, v101
	v_cvt_pk_bf16_f32 v100, v102, v103
	v_cvt_pk_bf16_f32 v101, v104, v105
	v_cvt_pk_bf16_f32 v102, v106, v107
	v_cvt_pk_bf16_f32 v103, v108, v109
	v_cvt_pk_bf16_f32 v104, v110, v111
	v_cvt_pk_bf16_f32 v105, v112, v113
	v_cvt_pk_bf16_f32 v106, v114, v115
	v_cvt_pk_bf16_f32 v107, v116, v117
	v_cvt_pk_bf16_f32 v108, v118, v119
	v_cvt_pk_bf16_f32 v109, v120, v121
	v_cvt_pk_bf16_f32 v110, v122, v123
	v_cvt_pk_bf16_f32 v111, v124, v125
	v_cvt_pk_bf16_f32 v112, v126, v127
	v_cvt_pk_bf16_f32 v113, v128, v129
	v_lshl_add_u64 v[204:205], v[204:205], 0, s[50:51]
	v_lshl_add_u64 v[206:207], v[206:207], 0, s[50:51]
	v_lshl_add_u64 v[208:209], v[208:209], 0, s[64:65]
	v_lshl_add_u64 v[210:211], v[210:211], 0, s[64:65]
	v_lshl_add_u64 v[212:213], v[212:213], 0, s[64:65]
	s_waitcnt lgkmcnt(0)
	v_mfma_f32_32x32x16_bf16 v[34:49], v[224:227], v[78:81], v[34:49]
	ds_read2_b64 v[220:223], v214 offset0:128 offset1:130
	ds_read2_b64 v[224:227], v216 offset0:128 offset1:130
	ds_read2_b64 v[230:233], v214 offset0:132 offset1:134
	s_waitcnt lgkmcnt(2)
	v_mfma_f32_32x32x16_bf16 v[18:33], v[220:223], v[98:101], v[18:33]
	ds_read2_b64 v[220:223], v216 offset0:132 offset1:134
	s_waitcnt lgkmcnt(2)
	v_mfma_f32_32x32x16_bf16 v[2:17], v[224:227], v[98:101], v[2:17]
	ds_read2_b64 v[224:227], v214 offset0:136 offset1:138
	s_waitcnt lgkmcnt(2)
	v_mfma_f32_32x32x16_bf16 v[18:33], v[230:233], v[102:105], v[18:33]
	ds_read2_b64 v[230:233], v216 offset0:136 offset1:138
	s_waitcnt lgkmcnt(2)
	v_mfma_f32_32x32x16_bf16 v[2:17], v[220:223], v[102:105], v[2:17]
	ds_read2_b64 v[220:223], v214 offset0:140 offset1:142
	s_waitcnt lgkmcnt(2)
	v_mfma_f32_32x32x16_bf16 v[18:33], v[224:227], v[106:109], v[18:33]
	ds_read2_b64 v[224:227], v216 offset0:140 offset1:142
	s_waitcnt lgkmcnt(2)
	v_mfma_f32_32x32x16_bf16 v[2:17], v[230:233], v[106:109], v[2:17]
	s_waitcnt lgkmcnt(1)
	v_mfma_f32_32x32x16_bf16 v[18:33], v[220:223], v[110:113], v[18:33]
	s_waitcnt lgkmcnt(0)
	v_mfma_f32_32x32x16_bf16 v[2:17], v[224:227], v[110:113], v[2:17]
	s_add_i32 s2, s2, -1
	s_cmp_eq_u32 s2, 0
	s_cbranch_scc0 .Latt_kt
	v_mov_b32_e32 v232, 0x47
